# ds_read hoisting (batched LDS reads, counted lgkmcnt) in P7a chunk_pre on top of deep-queue EpiResid epilogues
# speedup vs baseline: 1.0099x; 1.0031x over previous
; __device__ __forceinline__ void chunk_pre(const Params& p, LAS unsigned char* lds, int item, int next_item, int tid, int wave, int lane, h16 (&raw)[48]) {
;     ...
;     {
;         f32x4 acc[2];
;         acc[0] = (f32x4){0.f, 0.f, 0.f, 0.f}; acc[1] = acc[0]; mm64(Tb, AtT, acc, wave, fr, fq);
; #pragma unroll
;         for (int nt = 0; nt < 2; ++nt) st_bf4(AbT + ar * MS + 32 * (wave & 1) + 16 * nt + 4 * fq, acc[nt]);
;         acc[0] = (f32x4){0.f, 0.f, 0.f, 0.f}; acc[1] = acc[0]; mm64(Tb, RH2T, acc, wave, fr, fq);
; #pragma unroll
;         for (int nt = 0; nt < 2; ++nt) st_bf4(P1T + ar * MS + 32 * (wave & 1) + 16 * nt + 4 * fq, acc[nt]);
;     }
;     BAR_LDS();
;     {
;         f32x4 acc[2];
;         acc[0] = (f32x4){0.f, 0.f, 0.f, 0.f}; acc[1] = acc[0];
;         mm64(AbT, Mrb, acc, wave, fr, fq);
; #pragma unroll
;         for (int nt = 0; nt < 2; ++nt) { const int b0 = 32 * (wave & 1) + 16 * nt + 4 * fq; const u32x2 rw = *(const LAS u32x2*)(Rt + ar * MS + b0);
;             const f32x4 v = acc[nt] + (f32x4){bflo(rw.x), bfhi(rw.x), bflo(rw.y), bfhi(rw.y)};
;             u32x2 w; w.x = pk2(v.x, v.y); w.y = pk2(v.z, v.w); *(u32x2*)(base + (size_t)(ar * 6 + 2) * 64 + b0) = w; }
;         acc[0] = (f32x4){0.f, 0.f, 0.f, 0.f}; acc[1] = acc[0];
;         mm64(P1T, Mrb, acc, wave, fr, fq); mm64(VT, Mrk, acc, wave, fr, fq);
; #pragma unroll
;         for (int nt = 0; nt < 2; ++nt) { const int b0 = 32 * (wave & 1) + 16 * nt + 4 * fq; *(f32x4*)((float*)(base + (size_t)(ar * 6 + 3) * 64) + b0) = acc[nt]; }
;         acc[0] = (f32x4){0.f, 0.f, 0.f, 0.f}; acc[1] = acc[0];
;         mm64(AbT, BhT, acc, wave, fr, fq);
;         { float WL = 1.f;
; #pragma unroll
;           for (int q = 0; q < 8; ++q) WL *= GT[q * 64 + ar];
; #pragma unroll
;           for (int nt = 0; nt < 2; ++nt) { const int b0 = 32 * (wave & 1) + 16 * nt + 4 * fq; f32x4 v = acc[nt];
; #pragma unroll
;               for (int jj = 0; jj < 4; ++jj) if (b0 + jj == ar) v[jj] += WL;
;               u32x2 w; w.x = pk2(v.x, v.y); w.y = pk2(v.z, v.w); *(u32x2*)(base + (size_t)(ar * 6 + 0) * 64 + b0) = w; } }
;         acc[0] = (f32x4){0.f, 0.f, 0.f, 0.f}; acc[1] = acc[0];
;         mm64(BhT, P1T, acc, wave, fr, fq); mm64(KhT, VT, acc, wave, fr, fq);
; #pragma unroll
;         for (int nt = 0; nt < 2; ++nt) { const int b0 = 32 * (wave & 1) + 16 * nt + 4 * fq; const f32x4 v = acc[nt];
.LBB0_922:
	s_or_b64 exec, exec, s[12:13]
	s_waitcnt lgkmcnt(0)
	s_barrier
	ds_read_b128 v[4:7], v132
	ds_read_b128 v[8:11], v161
	ds_read_b128 v[12:15], v161 offset:2304
	ds_read_b128 v[212:215], v132 offset:64
	ds_read_b128 v[16:19], v161 offset:64
	ds_read_b128 v[216:219], v161 offset:2368
	s_ashr_i32 s12, s45, 7
	s_waitcnt lgkmcnt(4)
	v_mfma_f32_16x16x32_bf16 v[8:11], v[8:11], v[4:7], 0
	v_add_u32_e32 v20, 0x6800, v95
	s_ashr_i32 s13, s12, 31
	s_lshl_b32 s8, s45, 6
	s_waitcnt lgkmcnt(3)
	v_mfma_f32_16x16x32_bf16 v[4:7], v[12:15], v[4:7], 0
	s_nop 0
	s_nop 0
	s_lshl_b64 s[12:13], s[12:13], 13
	s_and_b32 s8, s8, 0x1fc0
	s_waitcnt lgkmcnt(1)
	v_mfma_f32_16x16x32_bf16 v[8:11], v[16:19], v[212:215], v[8:11]
	s_nop 0
	s_or_b32 s8, s12, s8
	s_mul_i32 s12, s13, 0x300
	s_nop 4
	v_cvt_pk_bf16_f32 v8, v8, v9
	s_waitcnt lgkmcnt(0)
	v_mfma_f32_16x16x32_bf16 v[4:7], v[216:219], v[212:215], v[4:7]
	v_cvt_pk_bf16_f32 v9, v10, v11
	s_mul_hi_u32 s13, s8, 0x300
	s_add_i32 s13, s13, s12
	s_nop 4
	v_cvt_pk_bf16_f32 v4, v4, v5
	v_cvt_pk_bf16_f32 v5, v6, v7
	v_add_u32_e32 v6, 0x2000, v159
	ds_write2_b64 v6, v[8:9], v[4:5] offset0:128 offset1:132
	ds_read_b128 v[4:7], v133
	ds_read_b128 v[8:11], v161
	ds_read_b128 v[12:15], v161 offset:2304
	s_waitcnt lgkmcnt(1)
	v_mfma_f32_16x16x32_bf16 v[8:11], v[8:11], v[4:7], 0
	s_mulk_i32 s8, 0x300
	s_add_u32 s80, s6, s8
	s_addc_u32 s81, s7, s13
	s_waitcnt lgkmcnt(0)
	v_mfma_f32_16x16x32_bf16 v[4:7], v[12:15], v[4:7], 0
	ds_read_b128 v[12:15], v133 offset:64
	ds_read_b128 v[16:19], v161 offset:64
	v_lshl_add_u64 v[180:181], s[80:81], 0, v[26:27]
	v_readlane_b32 s12, v244, 51
	s_waitcnt lgkmcnt(0)
	v_mfma_f32_16x16x32_bf16 v[8:11], v[16:19], v[12:15], v[8:11]
	ds_read_b128 v[16:19], v161 offset:2368
	v_readlane_b32 s13, v244, 52
	s_and_b64 vcc, exec, s[10:11]
	s_waitcnt lgkmcnt(0)
	v_mfma_f32_16x16x32_bf16 v[4:7], v[16:19], v[12:15], v[4:7]
	s_nop 2
	v_cvt_pk_bf16_f32 v8, v8, v9
	v_cvt_pk_bf16_f32 v9, v10, v11
	s_mov_b32 s45, s50
	s_nop 1
	v_cvt_pk_bf16_f32 v4, v4, v5
	v_cvt_pk_bf16_f32 v5, v6, v7
	v_add_u32_e32 v6, 0x4800, v159
	ds_write2_b64 v6, v[8:9], v[4:5] offset1:4
	s_waitcnt lgkmcnt(0)
	s_barrier
	ds_read_b128 v[36:39], v134
	ds_read_b128 v[8:11], v161 offset:9216
	ds_read_b128 v[16:19], v161 offset:11520
	ds_read_b128 v[168:171], v134 offset:64
	ds_read_b128 v[4:7], v161 offset:9280
	ds_read2_b64 v[176:179], v20 offset0:128 offset1:132
	ds_read_b128 v[212:215], v161 offset:11584
	ds_read_b128 v[216:219], v161 offset:18432
	ds_read_b128 v[220:223], v161 offset:20736
	ds_read_b128 v[224:227], v161 offset:18496
	ds_read_b128 v[228:231], v161 offset:20800
	ds_read_b128 v[232:235], v135
	ds_read_b128 v[236:239], v161 offset:55296
	ds_read_b128 v[240:243], v161 offset:57600
	s_waitcnt lgkmcnt(12)
	v_mfma_f32_16x16x32_bf16 v[12:15], v[8:11], v[36:39], 0
	s_nop 0
	s_waitcnt lgkmcnt(8)
	v_lshlrev_b32_e32 v34, 16, v176
	v_mfma_f32_16x16x32_bf16 v[172:175], v[4:7], v[168:171], v[12:15]
	v_and_b32_e32 v35, 0xffff0000, v176
	v_lshlrev_b32_e32 v176, 16, v177
	v_and_b32_e32 v177, 0xffff0000, v177
	s_nop 0
	s_nop 0
	v_mfma_f32_16x16x32_bf16 v[164:167], v[16:19], v[36:39], 0
	s_nop 1
	v_add_f32_e64 v34, v172, v34
	v_add_f32_e64 v35, v173, v35
	v_pk_add_f32 v[174:175], v[174:175], v[176:177]
	v_cvt_pk_bf16_f32 v172, v34, v35
	s_waitcnt lgkmcnt(7)
	v_mfma_f32_16x16x32_bf16 v[164:167], v[212:215], v[168:171], v[164:167]
	v_lshlrev_b64 v[34:35], 1, v[24:25]
	v_cvt_pk_bf16_f32 v173, v174, v175
	v_lshl_add_u64 v[174:175], v[180:181], 0, v[34:35]
	global_store_dwordx2 v[174:175], v[172:173], off
	v_lshlrev_b32_e32 v172, 16, v178
	v_and_b32_e32 v173, 0xffff0000, v178
	v_lshlrev_b32_e32 v176, 16, v179
	v_and_b32_e32 v177, 0xffff0000, v179
	v_pk_add_f32 v[166:167], v[166:167], v[176:177]
	v_pk_add_f32 v[164:165], v[164:165], v[172:173]
	s_nop 0
	v_cvt_pk_bf16_f32 v164, v164, v165
	v_cvt_pk_bf16_f32 v165, v166, v167
	global_store_dwordx2 v[174:175], v[164:165], off offset:32
	s_nop 0
	s_nop 0
	s_waitcnt lgkmcnt(6)
	v_mfma_f32_16x16x32_bf16 v[164:167], v[216:219], v[36:39], 0
	s_waitcnt lgkmcnt(5)
	v_mfma_f32_16x16x32_bf16 v[36:39], v[220:223], v[36:39], 0
	s_nop 0
	s_waitcnt lgkmcnt(4)
	v_mfma_f32_16x16x32_bf16 v[164:167], v[224:227], v[168:171], v[164:167]
	s_nop 0
	s_waitcnt lgkmcnt(3)
	v_mfma_f32_16x16x32_bf16 v[36:39], v[228:231], v[168:171], v[36:39]
	s_nop 0
	s_nop 0
	s_waitcnt lgkmcnt(1)
	v_mfma_f32_16x16x32_bf16 v[164:167], v[236:239], v[232:235], v[164:167]
	s_nop 0
	s_waitcnt lgkmcnt(0)
	v_mfma_f32_16x16x32_bf16 v[36:39], v[240:243], v[232:235], v[36:39]
	ds_read_b128 v[168:171], v135 offset:64
	ds_read_b128 v[172:175], v161 offset:55360
	s_waitcnt lgkmcnt(0)
	v_mfma_f32_16x16x32_bf16 v[164:167], v[172:175], v[168:171], v[164:167]
	ds_read_b128 v[172:175], v161 offset:57664
	ds_read_b128 v[216:219], v91 offset:36864
	s_waitcnt lgkmcnt(1)
	v_mfma_f32_16x16x32_bf16 v[36:39], v[172:175], v[168:171], v[36:39]
	v_lshl_add_u64 v[168:169], s[80:81], 0, v[28:29]
	v_lshl_add_u64 v[168:169], v[24:25], 2, v[168:169]
	s_nop 2
	global_store_dwordx4 v[168:169], v[164:167], off
	s_nop 1
	global_store_dwordx4 v[168:169], v[36:39], off offset:64
	s_nop 0
	s_waitcnt lgkmcnt(0)
	v_mfma_f32_16x16x32_bf16 v[8:11], v[8:11], v[216:219], 0
	v_mfma_f32_16x16x32_bf16 v[16:19], v[16:19], v[216:219], 0
	ds_read_b128 v[36:39], v91 offset:36928
	ds_read2st64_b32 v[216:217], v136 offset1:1
	ds_read2st64_b32 v[218:219], v136 offset0:2 offset1:3
	ds_read2st64_b32 v[220:221], v136 offset0:4 offset1:5
	ds_read2st64_b32 v[222:223], v136 offset0:6 offset1:7
	ds_read_b128 v[224:227], v91 offset:18432
	ds_read_b128 v[228:231], v161 offset:36864
	ds_read_b128 v[232:235], v161 offset:39168
	ds_read_b128 v[236:239], v91 offset:18496
	ds_read_b128 v[240:243], v161 offset:36928
	s_waitcnt lgkmcnt(9)
; #define BAR_LDS() do { asm volatile("s_waitcnt lgkmcnt(0)" ::: "memory"); __builtin_amdgcn_s_barrier(); asm volatile("" ::: "memory"); } while (0)
; __device__ __forceinline__ unsigned pk2(float lo, float hi) { const f32x2c v = {lo, hi}; const bf16x2c b = __builtin_convertvector(v, bf16x2c); return __builtin_bit_cast(unsigned, b); }
; __device__ __forceinline__ void chunk_pre(const Params& p, LAS unsigned char* lds, int item, int next_item, int tid, int wave, int lane, h16 (&raw)[48]) {
;     ...
;     {
;         const int g = tid >> 6, k = tid & 63;
;         float wv[8], lp[8];
; #pragma unroll
;         for (int i = 0; i < 8; ++i) wv[i] = (float)raw[i * 6 + 2];
;         lp[0] = wv[0];
; #pragma unroll
;         for (int i = 1; i < 8; ++i) lp[i] = lp[i - 1] * wv[i];
;         GT[g * 64 + k] = lp[7];
;         BAR_LDS();
;         float bs = 1.f, WL = 1.f;
; #pragma unroll
;         for (int q = 0; q < 8; ++q) { const float gq = GT[q * 64 + k]; if (q < g) bs *= gq; WL *= gq; }
;     ...
;         acc[0] = (f32x4){0.f, 0.f, 0.f, 0.f}; acc[1] = acc[0];
;         mm64(AbT, BhT, acc, wave, fr, fq);
;         { float WL = 1.f;
; #pragma unroll
;           for (int q = 0; q < 8; ++q) WL *= GT[q * 64 + ar];
; #pragma unroll
;           for (int nt = 0; nt < 2; ++nt) { const int b0 = 32 * (wave & 1) + 16 * nt + 4 * fq; f32x4 v = acc[nt];
; #pragma unroll
;               for (int jj = 0; jj < 4; ++jj) if (b0 + jj == ar) v[jj] += WL;
;               u32x2 w; w.x = pk2(v.x, v.y); w.y = pk2(v.z, v.w); *(u32x2*)(base + (size_t)(ar * 6 + 0) * 64 + b0) = w; } }
;         acc[0] = (f32x4){0.f, 0.f, 0.f, 0.f}; acc[1] = acc[0];
;         mm64(BhT, P1T, acc, wave, fr, fq); mm64(KhT, VT, acc, wave, fr, fq);
; #pragma unroll
;         for (int nt = 0; nt < 2; ++nt) { const int b0 = 32 * (wave & 1) + 16 * nt + 4 * fq; const f32x4 v = acc[nt];
;             u32x2 w; w.x = pk2(v.x, v.y); w.y = pk2(v.z, v.w); *(u32x2*)(base + (size_t)(ar * 6 + 1) * 64 + b0) = w; }
;     }
;     BAR_LDS();
	v_mfma_f32_16x16x32_bf16 v[4:7], v[4:7], v[36:39], v[8:11]
	v_mfma_f32_16x16x32_bf16 v[8:11], v[212:215], v[36:39], v[16:19]
	s_nop 0
	s_waitcnt lgkmcnt(8)
	v_mul_f32_e32 v14, v216, v217
	s_nop 0
	s_waitcnt lgkmcnt(7)
	v_mul_f32_e32 v12, v14, v218
	v_mul_f32_e32 v14, v12, v219
	s_nop 0
	s_waitcnt lgkmcnt(6)
	v_mul_f32_e32 v12, v14, v220
	v_mul_f32_e32 v14, v12, v221
	s_nop 0
	s_waitcnt lgkmcnt(5)
	v_mul_f32_e32 v12, v14, v222
	v_fma_f32 v16, v12, v223, v4
	v_cndmask_b32_e64 v4, v4, v16, s[12:13]
	v_readlane_b32 s12, v244, 53
	v_fma_f32 v16, v12, v223, v5
	v_readlane_b32 s13, v244, 54
	v_lshl_add_u64 v[14:15], s[80:81], 0, v[30:31]
	s_nop 0
	v_cndmask_b32_e64 v5, v5, v16, s[12:13]
	v_readlane_b32 s12, v244, 55
	v_fma_f32 v16, v12, v223, v6
	v_readlane_b32 s13, v244, 56
	v_cvt_pk_bf16_f32 v4, v4, v5
	s_nop 0
	v_cndmask_b32_e64 v6, v6, v16, s[12:13]
	v_fma_f32 v16, v12, v223, v7
	v_cndmask_b32_e64 v7, v7, v16, s[56:57]
	v_cvt_pk_bf16_f32 v5, v6, v7
	v_lshl_add_u64 v[6:7], v[14:15], 0, v[34:35]
	global_store_dwordx2 v[6:7], v[4:5], off
	v_fma_f32 v4, v12, v223, v8
	v_fma_f32 v5, v12, v223, v9
	v_cndmask_b32_e64 v4, v8, v4, s[88:89]
	v_cndmask_b32_e64 v5, v9, v5, s[4:5]
	v_fma_f32 v8, v12, v223, v10
	v_fma_f32 v9, v12, v223, v11
	v_cndmask_b32_e64 v8, v10, v8, s[0:1]
	v_cndmask_b32_e64 v9, v11, v9, s[68:69]
	v_cvt_pk_bf16_f32 v4, v4, v5
	v_cvt_pk_bf16_f32 v5, v8, v9
	global_store_dwordx2 v[6:7], v[4:5], off offset:32
	s_nop 0
	s_nop 0
	s_nop 0
	s_waitcnt lgkmcnt(3)
	v_mfma_f32_16x16x32_bf16 v[8:11], v[228:231], v[224:227], 0
	s_waitcnt lgkmcnt(2)
	v_mfma_f32_16x16x32_bf16 v[4:7], v[232:235], v[224:227], 0
	s_nop 0
	s_nop 0
	s_waitcnt lgkmcnt(0)
	v_mfma_f32_16x16x32_bf16 v[8:11], v[240:243], v[236:239], v[8:11]
	ds_read_b128 v[16:19], v161 offset:39232
	ds_read_b128 v[212:215], v91 offset:55296
	ds_read_b128 v[216:219], v161 offset:46080
	ds_read_b128 v[220:223], v161 offset:48384
	s_waitcnt lgkmcnt(3)
	v_mfma_f32_16x16x32_bf16 v[4:7], v[16:19], v[236:239], v[4:7]
	s_nop 0
	s_nop 0
	s_waitcnt lgkmcnt(1)
	v_mfma_f32_16x16x32_bf16 v[8:11], v[216:219], v[212:215], v[8:11]
	s_nop 0
	s_waitcnt lgkmcnt(0)
	v_mfma_f32_16x16x32_bf16 v[4:7], v[220:223], v[212:215], v[4:7]
	ds_read_b128 v[12:15], v91 offset:55360
	ds_read_b128 v[16:19], v161 offset:46144
	s_waitcnt lgkmcnt(0)
	v_mfma_f32_16x16x32_bf16 v[8:11], v[16:19], v[12:15], v[8:11]
	ds_read_b128 v[16:19], v161 offset:48448
	s_waitcnt lgkmcnt(0)
	v_mfma_f32_16x16x32_bf16 v[4:7], v[16:19], v[12:15], v[4:7]
	v_lshl_add_u64 v[12:13], s[80:81], 0, v[32:33]
	s_nop 3
	v_cvt_pk_bf16_f32 v8, v8, v9
	v_cvt_pk_bf16_f32 v9, v10, v11
	v_lshl_add_u64 v[10:11], v[12:13], 0, v[34:35]
	v_cvt_pk_bf16_f32 v4, v4, v5
	v_cvt_pk_bf16_f32 v5, v6, v7
	global_store_dwordx2 v[10:11], v[8:9], off
	global_store_dwordx2 v[10:11], v[4:5], off offset:32
	s_waitcnt lgkmcnt(0)
	s_barrier
	s_cbranch_vccnz .LBB0_945
.LBB0_923:
	s_waitcnt vmcnt(45)
	v_cvt_f32_f16_e32 v10, v42
	s_waitcnt vmcnt(39)
	v_cvt_f32_f16_e32 v4, v48
	s_waitcnt vmcnt(33)
	v_cvt_f32_f16_e32 v5, v54
	s_waitcnt vmcnt(27)
	v_cvt_f32_f16_e32 v6, v60
	s_waitcnt vmcnt(21)
	v_cvt_f32_f16_e32 v12, v68
	s_waitcnt vmcnt(15)
	v_cvt_f32_f16_e32 v13, v75
	v_mul_f32_e32 v11, v10, v4
	s_waitcnt vmcnt(9)
	v_cvt_f32_f16_e32 v14, v83
	v_mul_f32_e32 v34, v11, v5
	s_waitcnt vmcnt(3)
	v_cvt_f32_f16_e32 v15, v89
	v_mul_f32_e32 v35, v34, v6
	v_mul_f32_e32 v12, v35, v12
	v_mul_f32_e32 v13, v12, v13
	v_mul_f32_e32 v4, v13, v14
	v_mul_f32_e32 v5, v4, v15
	ds_write_b32 v63, v5
	s_waitcnt lgkmcnt(0)
	s_barrier
	ds_read2st64_b32 v[14:15], v65 offset1:1
	ds_read2st64_b32 v[212:213], v65 offset0:2 offset1:3
	ds_read2st64_b32 v[214:215], v65 offset0:4 offset1:5
	ds_read2st64_b32 v[216:217], v65 offset0:6 offset1:7
	v_readlane_b32 s14, v244, 33
	v_readlane_b32 s15, v244, 34
	v_cvt_f32_f16_e64 v37, -v40
	v_cvt_f32_f16_e32 v36, v41
	s_waitcnt lgkmcnt(3)
	v_cndmask_b32_e64 v6, 1.0, v14, s[82:83]
	v_mul_f32_e32 v16, v6, v15
	v_cndmask_b32_e64 v6, v6, v16, s[14:15]
	v_mul_f32_e32 v16, v14, v15
	s_nop 0
	v_readlane_b32 s14, v244, 35
	v_readlane_b32 s15, v244, 36
	v_cvt_f32_f16_e32 v17, v51
	v_cvt_f32_f16_e64 v170, -v46
	s_waitcnt lgkmcnt(2)
	v_mul_f32_e32 v168, v212, v6
	v_cndmask_b32_e64 v6, v6, v168, s[14:15]
	v_readlane_b32 s14, v244, 37
	v_mul_f32_e32 v14, v16, v212
	v_mul_f32_e32 v16, v213, v6
	v_readlane_b32 s15, v244, 38
	v_cvt_f32_f16_e32 v171, v47
	v_cvt_f32_f16_e32 v174, v53
	v_cndmask_b32_e64 v6, v6, v16, s[14:15]
	v_mul_f32_e32 v16, v14, v213
	s_nop 0
	v_readlane_b32 s14, v244, 39
	v_readlane_b32 s15, v244, 40
	v_cvt_f32_f16_e32 v18, v55
	v_cvt_f32_f16_e32 v19, v61
	s_waitcnt lgkmcnt(1)
	v_mul_f32_e32 v168, v214, v6
	v_cndmask_b32_e64 v6, v6, v168, s[14:15]
	v_readlane_b32 s14, v244, 41
	v_mul_f32_e32 v14, v16, v214
	v_mul_f32_e32 v16, v215, v6
	v_readlane_b32 s15, v244, 42
	v_cvt_f32_f16_e32 v176, v59
	v_cvt_f32_f16_e32 v177, v67
	v_cndmask_b32_e64 v6, v6, v16, s[14:15]
	v_mul_f32_e32 v16, v14, v215
	s_nop 0
	v_readlane_b32 s14, v244, 43
	v_readlane_b32 s15, v244, 44
	v_cvt_f32_f16_e32 v169, v73
	v_cvt_f32_f16_e32 v8, v69
	s_waitcnt lgkmcnt(0)
; __device__ __forceinline__ unsigned pk2(float lo, float hi) { const f32x2c v = {lo, hi}; const bf16x2c b = __builtin_convertvector(v, bf16x2c); return __builtin_bit_cast(unsigned, b); }
; __device__ __forceinline__ void chunk_pre(const Params& p, LAS unsigned char* lds, int item, int next_item, int tid, int wave, int lane, h16 (&raw)[48]) {
;     ...
;         float bhv[8], khv[8], vtv[8], atv[8];
; #pragma unroll
;         for (int i = 0; i < 8; ++i) {
;             const int t = 8 * g + i;
;             const float kk = (float)raw[i * 6 + 0], wr = (float)raw[i * 6 + 1], bb = (float)raw[i * 6 + 3], kx = (float)raw[i * 6 + 4], vv = (float)raw[i * 6 + 5];
;             const float Wt = bs * lp[i], Wp = (i == 0) ? bs : bs * lp[i - 1], iW = 1.f / Wt;
;             atv[i] = -kk * Wp; At[t * MS + k] = (bf16_t)(pk2(-kk * Wp, 0.f) & 0xffffu); Rt[t * MS + k] = (bf16_t)(pk2(wr * Wp, 0.f) & 0xffffu);
;             Bt[t * MS + k] = (bf16_t)(pk2(bb * iW, 0.f) & 0xffffu); Kt[t * MS + k] = (bf16_t)(pk2(kx * iW, 0.f) & 0xffffu);
;             bhv[i] = bb * iW * WL; khv[i] = kx * iW * WL; vtv[i] = vv;
;         }
	v_mul_f32_e32 v168, v216, v6
	v_cndmask_b32_e64 v6, v6, v168, s[14:15]
	v_readlane_b32 s14, v244, 45
	v_mul_f32_e32 v14, v16, v216
	v_mul_f32_e32 v16, v217, v6
	v_readlane_b32 s15, v244, 46
	v_cvt_f32_f16_e32 v9, v76
	v_cvt_f32_f16_e32 v7, v45
	v_cndmask_b32_e64 v16, v6, v16, s[14:15]
	v_mul_f32_e32 v168, v16, v37
	v_mul_f32_e32 v6, v14, v217
	v_cvt_pk_bf16_f32 v14, v168, s0
	ds_write_b16 v74, v14
	v_mul_f32_e32 v14, v16, v36
	v_pk_mul_f32 v[36:37], v[16:17], v[10:11] op_sel_hi:[0,1]
	v_div_scale_f32 v10, s[14:15], v37, v37, 1.0
	v_rcp_f32_e32 v11, v10
	v_cvt_pk_bf16_f32 v14, v14, s0
	ds_write_b16 v74, v14 offset:27648
	v_cvt_f32_f16_e32 v14, v43
	v_fma_f32 v172, -v10, v11, 1.0
	v_fmac_f32_e32 v11, v172, v11
	v_div_scale_f32 v172, vcc, 1.0, v37, 1.0
	v_mul_f32_e32 v173, v172, v11
	v_fma_f32 v175, -v10, v173, v172
	v_fmac_f32_e32 v173, v175, v11
	v_fma_f32 v10, -v10, v173, v172
	v_div_fmas_f32 v10, v10, v11, v173
	v_div_fixup_f32 v173, v10, v37, 1.0
	v_div_scale_f32 v10, s[14:15], v36, v36, 1.0
	v_rcp_f32_e32 v11, v10
	v_cvt_f32_f16_e32 v15, v49
	v_mul_f32_e32 v170, v36, v170
	v_pk_mul_f32 v[12:13], v[12:13], v[16:17] op_sel_hi:[1,0]
	v_fma_f32 v172, -v10, v11, 1.0
	v_fmac_f32_e32 v11, v172, v11
	v_div_scale_f32 v172, vcc, 1.0, v36, 1.0
	v_mul_f32_e32 v175, v172, v11
	v_fma_f32 v178, -v10, v175, v172
	v_fmac_f32_e32 v175, v178, v11
	v_fma_f32 v10, -v10, v175, v172
	v_div_fmas_f32 v10, v10, v11, v175
	v_div_fixup_f32 v172, v10, v36, 1.0
	v_pk_mul_f32 v[10:11], v[172:173], v[14:15]
	v_cvt_f32_f16_e32 v15, v50
	v_cvt_pk_bf16_f32 v14, v10, s0
	ds_write_b16 v74, v14 offset:9216
	v_cvt_pk_bf16_f32 v14, v170, s0
	ds_write_b16 v74, v14 offset:144
	v_mul_f32_e32 v14, v36, v171
	v_cvt_pk_bf16_f32 v14, v14, s0
	ds_write_b16 v74, v14 offset:27792
	v_cvt_pk_bf16_f32 v14, v11, s0
	ds_write_b16 v74, v14 offset:9360
	v_cvt_f32_f16_e32 v14, v44
	v_mul_f32_e32 v169, v12, v169
	v_cvt_pk_bf16_f32 v169, v169, s0
	ds_write_b16 v74, v169 offset:28368
	v_pk_mul_f32 v[14:15], v[172:173], v[14:15]
	v_pk_mul_f32 v[172:173], v[34:35], v[16:17] op_sel_hi:[1,0]
	v_cvt_pk_bf16_f32 v171, v14, s0
	v_div_scale_f32 v34, s[14:15], v173, v173, 1.0
	v_rcp_f32_e32 v35, v34
	ds_write_b16 v74, v171 offset:18432
	v_cvt_pk_bf16_f32 v171, v15, s0
	ds_write_b16 v74, v171 offset:18576
	v_mul_f32_e32 v171, v37, v174
	v_cvt_pk_bf16_f32 v171, v171, s0
	ds_write_b16 v74, v171 offset:27936
	v_fma_f32 v171, -v34, v35, 1.0
	v_fmac_f32_e32 v35, v171, v35
	v_div_scale_f32 v171, vcc, 1.0, v173, 1.0
	v_mul_f32_e32 v174, v171, v35
	v_fma_f32 v175, -v34, v174, v171
	v_fmac_f32_e32 v174, v175, v35
	v_fma_f32 v34, -v34, v174, v171
	v_div_fmas_f32 v34, v34, v35, v174
	v_div_fixup_f32 v175, v34, v173, 1.0
	v_div_scale_f32 v34, s[14:15], v172, v172, 1.0
	v_rcp_f32_e32 v35, v34
	v_pk_mov_b32 v[36:37], v[36:37], v[172:173] op_sel:[1,0]
	v_cvt_f32_f16_e32 v167, v82
	v_pk_mul_f32 v[4:5], v[4:5], v[16:17] op_sel_hi:[1,0]
	v_fma_f32 v171, -v34, v35, 1.0
	v_fmac_f32_e32 v35, v171, v35
	v_div_scale_f32 v171, vcc, 1.0, v172, 1.0
	v_mul_f32_e32 v174, v171, v35
	v_fma_f32 v178, -v34, v174, v171
	v_fmac_f32_e32 v174, v178, v35
	v_fma_f32 v34, -v34, v174, v171
	v_div_fmas_f32 v34, v34, v35, v174
	v_div_fixup_f32 v174, v34, v172, 1.0
	v_pk_mul_f32 v[34:35], v[174:175], v[18:19]
	v_cvt_f32_f16_e64 v19, -v58
	v_cvt_pk_bf16_f32 v18, v34, s0
	ds_write_b16 v74, v18 offset:9504
	v_cvt_f32_f16_e64 v18, -v52
	v_div_scale_f32 v16, s[14:15], v5, v5, 1.0
	v_cvt_f32_f16_e32 v166, v88
	v_pk_mul_f32 v[18:19], v[36:37], v[18:19]
	v_cvt_f32_f16_e32 v37, v62
	v_cvt_pk_bf16_f32 v36, v18, s0
	ds_write_b16 v74, v36 offset:288
	v_cvt_pk_bf16_f32 v36, v19, s0
	ds_write_b16 v74, v36 offset:432
	v_mul_f32_e32 v36, v172, v176
	v_cvt_pk_bf16_f32 v36, v36, s0
	ds_write_b16 v74, v36 offset:28080
	v_cvt_pk_bf16_f32 v36, v35, s0
	ds_write_b16 v74, v36 offset:9648
	v_cvt_f32_f16_e32 v36, v56
	v_cvt_f32_f16_e64 v180, -v81
	v_cvt_f32_f16_e64 v181, -v87
	v_cvt_f32_f16_e32 v20, v57
	v_pk_mul_f32 v[36:37], v[174:175], v[36:37]
	v_cvt_f32_f16_e32 v38, v64
	v_cvt_pk_bf16_f32 v171, v36, s0
	ds_write_b16 v74, v171 offset:18720
	v_cvt_pk_bf16_f32 v171, v37, s0
	ds_write_b16 v74, v171 offset:18864
	v_mul_f32_e32 v171, v173, v177
	v_cvt_pk_bf16_f32 v171, v171, s0
	ds_write_b16 v74, v171 offset:28224
	v_div_scale_f32 v171, s[14:15], v13, v13, 1.0
	v_rcp_f32_e32 v174, v171
	v_pk_mov_b32 v[172:173], v[172:173], v[12:13] op_sel:[1,0]
	v_cvt_f32_f16_e32 v39, v71
	v_cvt_f32_f16_e32 v163, v80
	v_fma_f32 v175, -v171, v174, 1.0
	v_fmac_f32_e32 v174, v175, v174
	v_div_scale_f32 v175, vcc, 1.0, v13, 1.0
	v_mul_f32_e32 v176, v175, v174
	v_fma_f32 v177, -v171, v176, v175
	v_fmac_f32_e32 v176, v177, v174
	v_fma_f32 v171, -v171, v176, v175
	v_div_fmas_f32 v171, v171, v174, v176
	v_div_fixup_f32 v175, v171, v13, 1.0
	v_div_scale_f32 v171, s[14:15], v12, v12, 1.0
	v_rcp_f32_e32 v174, v171
	v_cvt_f32_f16_e32 v164, v86
	s_waitcnt vmcnt(0)
; #define LAS __attribute__((address_space(3)))
; __device__ __forceinline__ unsigned pk2(float lo, float hi) { const f32x2c v = {lo, hi}; const bf16x2c b = __builtin_convertvector(v, bf16x2c); return __builtin_bit_cast(unsigned, b); }
; __device__ __forceinline__ h16* chunk_base(const Params& p, int item) { return (h16*)(p.ws + WS_SC) + ((size_t)(item >> 7) * SEQ + (size_t)(item & 127) * 64) * 384; }
; __device__ __forceinline__ void chunk_load(const Params& p, int item, int tid, h16 (&raw)[48]) {
;     const h16* base = chunk_base(p, item) + (size_t)(8 * (tid >> 6)) * 384 + (tid & 63);
; #pragma unroll
;     for (int i = 0; i < 8; ++i)
; #pragma unroll
;         for (int vq = 0; vq < 6; ++vq) raw[i * 6 + vq] = base[(size_t)i * 384 + vq * 64];
; }
; __device__ __forceinline__ void chunk_pre(const Params& p, LAS unsigned char* lds, int item, int next_item, int tid, int wave, int lane, h16 (&raw)[48]) {
;     ...
;         float bhv[8], khv[8], vtv[8], atv[8];
; #pragma unroll
;         for (int i = 0; i < 8; ++i) {
;             const int t = 8 * g + i;
;             const float kk = (float)raw[i * 6 + 0], wr = (float)raw[i * 6 + 1], bb = (float)raw[i * 6 + 3], kx = (float)raw[i * 6 + 4], vv = (float)raw[i * 6 + 5];
;             const float Wt = bs * lp[i], Wp = (i == 0) ? bs : bs * lp[i - 1], iW = 1.f / Wt;
;             atv[i] = -kk * Wp; At[t * MS + k] = (bf16_t)(pk2(-kk * Wp, 0.f) & 0xffffu); Rt[t * MS + k] = (bf16_t)(pk2(wr * Wp, 0.f) & 0xffffu);
;             Bt[t * MS + k] = (bf16_t)(pk2(bb * iW, 0.f) & 0xffffu); Kt[t * MS + k] = (bf16_t)(pk2(kx * iW, 0.f) & 0xffffu);
;             bhv[i] = bb * iW * WL; khv[i] = kx * iW * WL; vtv[i] = vv;
;         }
;         *(LAS u32x4*)(BhT + k * MS + 8 * g) = (u32x4){pk2(bhv[0], bhv[1]), pk2(bhv[2], bhv[3]), pk2(bhv[4], bhv[5]), pk2(bhv[6], bhv[7])};
;         *(LAS u32x4*)(KhT + k * MS + 8 * g) = (u32x4){pk2(khv[0], khv[1]), pk2(khv[2], khv[3]), pk2(khv[4], khv[5]), pk2(khv[6], khv[7])};
;         *(LAS u32x4*)(VT + k * MS + 8 * g) = (u32x4){pk2(vtv[0], vtv[1]), pk2(vtv[2], vtv[3]), pk2(vtv[4], vtv[5]), pk2(vtv[6], vtv[7])};
;         *(LAS u32x4*)(AtT + k * MS + 8 * g) = (u32x4){pk2(atv[0], atv[1]), pk2(atv[2], atv[3]), pk2(atv[4], atv[5]), pk2(atv[6], atv[7])};
;     }
;     if (next_item >= 0) chunk_load(p, next_item, tid, raw);
	v_cvt_f32_f16_e32 v165, v93
	s_add_i32 s50, s45, s94
	v_fma_f32 v176, -v171, v174, 1.0
	v_fmac_f32_e32 v174, v176, v174
	v_div_scale_f32 v176, vcc, 1.0, v12, 1.0
	v_mul_f32_e32 v177, v176, v174
	v_fma_f32 v178, -v171, v177, v176
	v_fmac_f32_e32 v177, v178, v174
	v_fma_f32 v171, -v171, v177, v176
	v_div_fmas_f32 v171, v171, v174, v177
	v_cvt_f32_f16_e64 v176, -v66
	v_cvt_f32_f16_e64 v177, -v72
	v_div_fixup_f32 v174, v171, v12, 1.0
	v_pk_mul_f32 v[8:9], v[174:175], v[8:9]
	s_cmpk_gt_i32 s50, 0xfff
	v_cvt_pk_bf16_f32 v171, v8, s0
	v_pk_mul_f32 v[172:173], v[172:173], v[176:177]
	v_cvt_pk_bf16_f32 v169, v9, s0
	v_pk_mul_f32 v[176:177], v[6:7], v[8:9] op_sel_hi:[0,1]
	v_cvt_f32_f16_e32 v8, v70
	v_cvt_f32_f16_e32 v9, v78
	ds_write_b16 v74, v169 offset:9936
	ds_write_b16 v74, v171 offset:9792
	v_cvt_pk_bf16_f32 v171, v172, s0
	v_pk_mul_f32 v[8:9], v[174:175], v[8:9]
	ds_write_b16 v74, v171 offset:576
	v_cvt_pk_bf16_f32 v169, v8, s0
	v_pk_mul_f32 v[174:175], v[6:7], v[8:9] op_sel_hi:[0,1]
	v_mul_f32_e32 v8, v13, v167
	v_rcp_f32_e32 v167, v16
	ds_write_b16 v74, v169 offset:19008
	v_cvt_pk_bf16_f32 v169, v9, s0
	ds_write_b16 v74, v169 offset:19152
	v_fma_f32 v169, -v16, v167, 1.0
	v_cvt_pk_bf16_f32 v171, v173, s0
	v_fmac_f32_e32 v167, v169, v167
	v_div_scale_f32 v169, vcc, 1.0, v5, 1.0
	ds_write_b16 v74, v171 offset:720
	v_mul_f32_e32 v171, v169, v167
	v_fma_f32 v178, -v16, v171, v169
	v_fmac_f32_e32 v171, v178, v167
	v_fma_f32 v16, -v16, v171, v169
	v_div_fmas_f32 v16, v16, v167, v171
	v_div_fixup_f32 v179, v16, v5, 1.0
	v_div_scale_f32 v16, s[14:15], v4, v4, 1.0
	v_rcp_f32_e32 v167, v16
	v_cvt_pk_bf16_f32 v8, v8, s0
	ds_write_b16 v74, v8 offset:28512
	v_cvt_f32_f16_e32 v8, v84
	v_fma_f32 v169, -v16, v167, 1.0
	v_fmac_f32_e32 v167, v169, v167
	v_div_scale_f32 v169, vcc, 1.0, v4, 1.0
	v_mul_f32_e32 v171, v169, v167
	v_fma_f32 v178, -v16, v171, v169
	v_cvt_f32_f16_e32 v9, v90
	v_fmac_f32_e32 v171, v178, v167
	v_fma_f32 v16, -v16, v171, v169
	v_div_fmas_f32 v16, v16, v167, v171
	v_pk_mov_b32 v[12:13], v[12:13], v[4:5] op_sel:[1,0]
	v_div_fixup_f32 v178, v16, v4, 1.0
	v_pk_mul_f32 v[12:13], v[12:13], v[180:181]
	v_mul_f32_e32 v4, v4, v166
	v_pk_mul_f32 v[8:9], v[178:179], v[8:9]
	v_cvt_pk_bf16_f32 v5, v12, s0
	v_cvt_pk_bf16_f32 v4, v4, s0
	ds_write_b16 v74, v5 offset:864
	v_cvt_pk_bf16_f32 v5, v13, s0
	ds_write_b16 v74, v4 offset:28656
	v_cvt_pk_bf16_f32 v4, v9, s0
	v_cvt_pk_bf16_f32 v16, v8, s0
	ds_write_b16 v74, v5 offset:1008
	ds_write_b16 v74, v4 offset:10224
	v_pk_mul_f32 v[4:5], v[6:7], v[8:9] op_sel_hi:[0,1]
	v_cvt_f32_f16_e32 v8, v85
	v_cvt_f32_f16_e32 v9, v92
	s_cselect_b64 s[10:11], -1, 0
	s_cmpk_lt_i32 s50, 0x1000
	v_pk_mul_f32 v[10:11], v[6:7], v[10:11] op_sel_hi:[0,1]
	v_pk_mul_f32 v[8:9], v[178:179], v[8:9]
	v_pk_mul_f32 v[34:35], v[6:7], v[34:35] op_sel_hi:[0,1]
	ds_write_b16 v74, v16 offset:10080
	v_cvt_pk_bf16_f32 v16, v8, s0
	s_cselect_b32 s12, s50, -1
	v_pk_mul_f32 v[14:15], v[6:7], v[14:15] op_sel_hi:[0,1]
	v_pk_mul_f32 v[36:37], v[6:7], v[36:37] op_sel_hi:[0,1]
	ds_write_b16 v74, v16 offset:19296
	v_cvt_pk_bf16_f32 v16, v9, s0
	v_pk_mul_f32 v[166:167], v[6:7], v[8:9] op_sel_hi:[0,1]
	v_cvt_pk_bf16_f32 v8, v10, v11
	v_cvt_pk_bf16_f32 v9, v34, v35
	v_cvt_pk_bf16_f32 v10, v176, v177
	v_cvt_pk_bf16_f32 v11, v4, v5
	v_cvt_pk_bf16_f32 v4, v7, v17
	v_cvt_pk_bf16_f32 v5, v20, v38
	v_cvt_pk_bf16_f32 v6, v39, v163
	v_cvt_pk_bf16_f32 v7, v164, v165
	ds_write_b16 v74, v16 offset:19440
	ds_write_b128 v77, v[8:11] offset:36864
	v_cvt_pk_bf16_f32 v8, v14, v15
	v_cvt_pk_bf16_f32 v9, v36, v37
	v_cvt_pk_bf16_f32 v10, v174, v175
	v_cvt_pk_bf16_f32 v11, v166, v167
	ds_write_b128 v77, v[4:7] offset:55296
	v_cvt_pk_bf16_f32 v4, v168, v170
	v_cvt_pk_bf16_f32 v5, v18, v19
	v_cvt_pk_bf16_f32 v6, v172, v173
	v_cvt_pk_bf16_f32 v7, v12, v13
	s_cmp_lt_i32 s12, 0
	ds_write_b128 v77, v[8:11] offset:46080
	ds_write_b128 v79, v[4:7]
	s_cbranch_scc1 .LBB0_925
	s_lshr_b32 s8, s12, 7
	s_lshl_b64 s[14:15], s[8:9], 13
	s_lshl_b32 s8, s12, 6
	s_and_b32 s8, s8, 0x1fc0
	s_or_b32 s8, s14, s8
	v_mad_u64_u32 v[4:5], s[12:13], s8, v160, v[22:23]
	s_mul_i32 s8, s15, 0x300
	v_add_u32_e32 v5, s8, v5
	global_load_ushort v40, v[4:5], off
	global_load_ushort v41, v[4:5], off offset:128
	global_load_ushort v42, v[4:5], off offset:256
	global_load_ushort v43, v[4:5], off offset:384
	global_load_ushort v44, v[4:5], off offset:512
	global_load_ushort v45, v[4:5], off offset:640
	global_load_ushort v46, v[4:5], off offset:768
	global_load_ushort v47, v[4:5], off offset:896
	global_load_ushort v48, v[4:5], off offset:1024
	global_load_ushort v49, v[4:5], off offset:1152
	global_load_ushort v50, v[4:5], off offset:1280
	global_load_ushort v51, v[4:5], off offset:1408
	global_load_ushort v52, v[4:5], off offset:1536
	global_load_ushort v53, v[4:5], off offset:1664
	global_load_ushort v54, v[4:5], off offset:1792
	global_load_ushort v55, v[4:5], off offset:1920
	global_load_ushort v56, v[4:5], off offset:2048
	global_load_ushort v57, v[4:5], off offset:2176
	global_load_ushort v58, v[4:5], off offset:2304
	global_load_ushort v59, v[4:5], off offset:2432
	global_load_ushort v60, v[4:5], off offset:2560
	global_load_ushort v61, v[4:5], off offset:2688
	global_load_ushort v62, v[4:5], off offset:2816
	global_load_ushort v64, v[4:5], off offset:2944
	global_load_ushort v66, v[4:5], off offset:3072
	global_load_ushort v67, v[4:5], off offset:3200
	global_load_ushort v68, v[4:5], off offset:3328
	global_load_ushort v69, v[4:5], off offset:3456
	global_load_ushort v70, v[4:5], off offset:3584
	global_load_ushort v71, v[4:5], off offset:3712
	global_load_ushort v72, v[4:5], off offset:3840
	global_load_ushort v73, v[4:5], off offset:3968
	v_add_co_u32_e32 v4, vcc, s53, v4
	s_nop 1
	v_addc_co_u32_e32 v5, vcc, 0, v5, vcc
	global_load_ushort v75, v[4:5], off
	global_load_ushort v76, v[4:5], off offset:128
	global_load_ushort v78, v[4:5], off offset:256
	global_load_ushort v80, v[4:5], off offset:384
	global_load_ushort v81, v[4:5], off offset:512
	global_load_ushort v82, v[4:5], off offset:640
	global_load_ushort v83, v[4:5], off offset:768
	global_load_ushort v84, v[4:5], off offset:896
	global_load_ushort v85, v[4:5], off offset:1024
	global_load_ushort v86, v[4:5], off offset:1152
	global_load_ushort v87, v[4:5], off offset:1280
	global_load_ushort v88, v[4:5], off offset:1408
	global_load_ushort v89, v[4:5], off offset:1536
	global_load_ushort v90, v[4:5], off offset:1664
	global_load_ushort v92, v[4:5], off offset:1792
	global_load_ushort v93, v[4:5], off offset:1920
; #define LAS __attribute__((address_space(3)))
; #define BAR_LDS() do { asm volatile("s_waitcnt lgkmcnt(0)" ::: "memory"); __builtin_amdgcn_s_barrier(); asm volatile("" ::: "memory"); } while (0)
; __device__ __forceinline__ void st_bf4(LAS bf16_t* p, f32x4 v) { u32x2 w; w.x = pk2(v.x, v.y); w.y = pk2(v.z, v.w); *(LAS u32x2*)p = w; }
; __device__ __forceinline__ void chunk_pre(const Params& p, LAS unsigned char* lds, int item, int next_item, int tid, int wave, int lane, h16 (&raw)[48]) {
;     ...
;     BAR_LDS();
;     const int a0 = 16 * (wave >> 1), ar = a0 + fr;
;     {
;         f32x4 acc[2];
; #pragma unroll
;         for (int which = 0; which < 4; ++which) {
;             acc[0] = (f32x4){0.f, 0.f, 0.f, 0.f}; acc[1] = acc[0];
;             mm64((which & 1) ? Kt : Bt, (which & 2) ? Rt : At, acc, wave, fr, fq);
; #pragma unroll
;             for (int nt = 0; nt < 2; ++nt) { const int s0 = 32 * (wave & 1) + 16 * nt + 4 * fq; f32x4 v = acc[nt];
; #pragma unroll
;                 for (int jj = 0; jj < 4; ++jj) { const bool keep = (which & 2) ? (s0 + jj <= ar) : (s0 + jj < ar); if (!keep) v[jj] = 0.f; }
;                 if (which == 0) *(LAS f32x4*)(Mab + ar * 64 + s0) = v;
;                 else st_bf4(((which == 1) ? Mak : (which == 2) ? Mrb : Mrk) + ar * MS + s0, v); }
;         }
;     }
;     BAR_LDS();
;     {
;         f32x4 acc[2]; acc[0] = (f32x4){0.f, 0.f, 0.f, 0.f}; acc[1] = acc[0];
;         mm64(Mak, VT, acc, wave, fr, fq);
; #pragma unroll
;         for (int nt = 0; nt < 2; ++nt) st_bf4(RH2T + ar * MS + 32 * (wave & 1) + 16 * nt + 4 * fq, acc[nt]);
;     }
;     for (int e = tid; e < 6 * 256; e += 512) { const int ub = e >> 8, i = (e >> 4) & 15, j = e & 15;
;         const int r = ub < 3 ? 0 : ub < 5 ? 1 : 2, c = ub < 3 ? ub + 1 : ub < 5 ? ub - 1 : 3; Tb[(16 * r + i) * MS + 16 * c + j] = 0; }
;     if (tid < 64) {
.LBB0_925:
	s_waitcnt lgkmcnt(0)
	s_barrier
	ds_read_b128 v[4:7], v91
	ds_read_b128 v[8:11], v161 offset:9216
	ds_read_b128 v[12:15], v161 offset:11520
	ds_read_b128 v[212:215], v91 offset:64
	ds_read_b128 v[16:19], v161 offset:9280
	ds_read_b128 v[216:219], v161 offset:11584
	s_or_b64 vcc, s[72:73], s[20:21]
	s_waitcnt lgkmcnt(4)
	v_mfma_f32_16x16x32_bf16 v[8:11], v[8:11], v[4:7], 0
	s_or_b64 s[80:81], s[76:77], s[24:25]
	s_waitcnt lgkmcnt(3)
	v_mfma_f32_16x16x32_bf16 v[4:7], v[12:15], v[4:7], 0
	s_nop 0
	s_nop 0
	s_waitcnt lgkmcnt(1)
	v_mfma_f32_16x16x32_bf16 v[8:11], v[16:19], v[212:215], v[8:11]
	s_nop 0
	s_waitcnt lgkmcnt(0)
	v_mfma_f32_16x16x32_bf16 v[4:7], v[216:219], v[212:215], v[4:7]
	s_nop 4
	v_cndmask_b32_e64 v11, 0, v11, s[22:23]
	v_cndmask_b32_e64 v10, 0, v10, s[70:71]
	v_cndmask_b32_e64 v9, 0, v9, s[72:73]
	v_cndmask_b32_e32 v8, 0, v8, vcc
	v_cndmask_b32_e64 v7, 0, v7, s[26:27]
	v_cndmask_b32_e64 v6, 0, v6, s[74:75]
	v_cndmask_b32_e64 v5, 0, v5, s[76:77]
	v_cndmask_b32_e64 v4, 0, v4, s[80:81]
	ds_write_b128 v94, v[8:11]
	ds_write_b128 v94, v[4:7] offset:64
	ds_read_b128 v[4:7], v91
	ds_read_b128 v[8:11], v161 offset:18432
	ds_read_b128 v[12:15], v161 offset:20736
	ds_read_b128 v[212:215], v91 offset:64
	ds_read_b128 v[16:19], v161 offset:18496
	ds_read_b128 v[216:219], v161 offset:20800
	s_waitcnt lgkmcnt(4)
	v_mfma_f32_16x16x32_bf16 v[8:11], v[8:11], v[4:7], 0
	s_waitcnt lgkmcnt(3)
	v_mfma_f32_16x16x32_bf16 v[4:7], v[12:15], v[4:7], 0
	s_nop 0
	s_nop 0
	s_waitcnt lgkmcnt(1)
	v_mfma_f32_16x16x32_bf16 v[8:11], v[16:19], v[212:215], v[8:11]
	s_nop 0
	s_waitcnt lgkmcnt(0)
	v_mfma_f32_16x16x32_bf16 v[4:7], v[216:219], v[212:215], v[4:7]
	s_nop 4
	v_cndmask_b32_e64 v11, 0, v11, s[22:23]
	v_cndmask_b32_e64 v10, 0, v10, s[70:71]
	v_cndmask_b32_e64 v9, 0, v9, s[72:73]
	v_cndmask_b32_e32 v8, 0, v8, vcc
	v_cndmask_b32_e64 v7, 0, v7, s[26:27]
	v_cndmask_b32_e64 v6, 0, v6, s[74:75]
	v_cndmask_b32_e64 v5, 0, v5, s[76:77]
	v_cndmask_b32_e64 v4, 0, v4, s[80:81]
	v_cvt_pk_bf16_f32 v8, v8, v9
	v_cvt_pk_bf16_f32 v9, v10, v11
	v_cvt_pk_bf16_f32 v4, v4, v5
	v_cvt_pk_bf16_f32 v5, v6, v7
	v_add_u32_e32 v6, 0xf800, v95
	ds_write2_b64 v6, v[8:9], v[4:5] offset0:128 offset1:132
	ds_read_b128 v[4:7], v91 offset:27648
	ds_read_b128 v[8:11], v161 offset:9216
	ds_read_b128 v[12:15], v161 offset:11520
	ds_read_b128 v[212:215], v91 offset:27712
	ds_read_b128 v[16:19], v161 offset:9280
	ds_read_b128 v[216:219], v161 offset:11584
	s_waitcnt lgkmcnt(4)
	v_mfma_f32_16x16x32_bf16 v[8:11], v[8:11], v[4:7], 0
	s_waitcnt lgkmcnt(3)
	v_mfma_f32_16x16x32_bf16 v[4:7], v[12:15], v[4:7], 0
	s_nop 0
	s_nop 0
	s_waitcnt lgkmcnt(1)
	v_mfma_f32_16x16x32_bf16 v[8:11], v[16:19], v[212:215], v[8:11]
	s_nop 0
	s_waitcnt lgkmcnt(0)
	v_mfma_f32_16x16x32_bf16 v[4:7], v[216:219], v[212:215], v[4:7]
	v_mov_b32_e32 v12, s9
	s_nop 3
	v_cndmask_b32_e64 v12, v8, v12, s[28:29]
	v_cndmask_b32_e64 v8, v12, v8, s[20:21]
	v_cndmask_b32_e64 v9, 0, v9, s[20:21]
	v_cndmask_b32_e64 v12, v10, 0, s[30:31]
	v_cvt_pk_bf16_f32 v10, v8, v9
	v_mov_b32_e32 v8, s9
	v_cndmask_b32_e64 v8, v4, v8, s[36:37]
	v_cndmask_b32_e64 v11, v11, 0, s[34:35]
	v_cndmask_b32_e64 v4, v8, v4, s[24:25]
	v_cndmask_b32_e64 v5, 0, v5, s[24:25]
	v_cndmask_b32_e64 v6, v6, 0, s[38:39]
	v_cndmask_b32_e64 v7, v7, 0, s[40:41]
	v_cvt_pk_bf16_f32 v11, v12, v11
	v_cvt_pk_bf16_f32 v4, v4, v5
	v_cvt_pk_bf16_f32 v5, v6, v7
	ds_write2_b64 v96, v[10:11], v[4:5] offset1:4
	ds_read_b128 v[4:7], v91 offset:27648
	ds_read_b128 v[8:11], v161 offset:18432
	ds_read_b128 v[12:15], v161 offset:20736
	s_waitcnt lgkmcnt(1)
	v_mfma_f32_16x16x32_bf16 v[8:11], v[8:11], v[4:7], 0
	s_waitcnt lgkmcnt(0)
	v_mfma_f32_16x16x32_bf16 v[4:7], v[12:15], v[4:7], 0
	ds_read_b128 v[12:15], v91 offset:27712
	ds_read_b128 v[16:19], v161 offset:18496
	s_waitcnt lgkmcnt(0)
	v_mfma_f32_16x16x32_bf16 v[8:11], v[16:19], v[12:15], v[8:11]
	ds_read_b128 v[16:19], v161 offset:20800
	s_waitcnt lgkmcnt(0)
	v_mfma_f32_16x16x32_bf16 v[4:7], v[16:19], v[12:15], v[4:7]
	v_mov_b32_e32 v12, s9
	s_nop 3
	v_cndmask_b32_e64 v12, v8, v12, s[28:29]
	v_cndmask_b32_e64 v8, v12, v8, s[20:21]
	v_cndmask_b32_e64 v9, 0, v9, s[20:21]
	v_cndmask_b32_e64 v12, v10, 0, s[30:31]
	v_cvt_pk_bf16_f32 v10, v8, v9
	v_mov_b32_e32 v8, s9
	v_cndmask_b32_e64 v8, v4, v8, s[36:37]
	v_cndmask_b32_e64 v11, v11, 0, s[34:35]
	v_cndmask_b32_e64 v4, v8, v4, s[24:25]
	v_cndmask_b32_e64 v5, 0, v5, s[24:25]
	v_cndmask_b32_e64 v6, v6, 0, s[38:39]
	v_cndmask_b32_e64 v7, v7, 0, s[40:41]
	v_cvt_pk_bf16_f32 v11, v12, v11
	v_cvt_pk_bf16_f32 v4, v4, v5
	v_cvt_pk_bf16_f32 v5, v6, v7
	ds_write2_b64 v97, v[10:11], v[4:5] offset1:4
	s_waitcnt lgkmcnt(0)
	s_barrier
	ds_read_b128 v[4:7], v91 offset:55296
	ds_read_b128 v[8:11], v161 offset:64512
	ds_read_b128 v[12:15], v139 offset:64512
	s_waitcnt lgkmcnt(1)
	v_mfma_f32_16x16x32_bf16 v[8:11], v[8:11], v[4:7], 0
	s_waitcnt lgkmcnt(0)
	v_mfma_f32_16x16x32_bf16 v[4:7], v[12:15], v[4:7], 0
	ds_read_b128 v[12:15], v91 offset:55360
	ds_read_b128 v[16:19], v161 offset:64576
	s_waitcnt lgkmcnt(0)
	v_mfma_f32_16x16x32_bf16 v[8:11], v[16:19], v[12:15], v[8:11]
	ds_read_b128 v[16:19], v139 offset:64576
	s_waitcnt lgkmcnt(0)
	v_mfma_f32_16x16x32_bf16 v[4:7], v[16:19], v[12:15], v[4:7]
	s_nop 4
	v_cvt_pk_bf16_f32 v8, v8, v9
	v_cvt_pk_bf16_f32 v9, v10, v11
	s_nop 0
	v_cvt_pk_bf16_f32 v4, v4, v5
	v_cvt_pk_bf16_f32 v5, v6, v7
	ds_write2_b64 v140, v[8:9], v[4:5] offset1:4
	s_mov_b64 s[12:13], exec
	v_readlane_b32 s14, v244, 47
	v_readlane_b32 s15, v244, 48
	s_and_b64 s[14:15], s[12:13], s[14:15]
	s_mov_b64 exec, s[14:15]
	s_cbranch_execz .LBB0_933
	v_readlane_b32 s54, v244, 57
	s_mov_b64 s[16:17], -1
	v_mov_b32_e32 v4, v0
	v_readlane_b32 s55, v244, 58
	s_and_saveexec_b64 s[14:15], s[54:55]
	s_cbranch_execz .LBB0_930
	v_mov_b64_e32 v[6:7], v[2:3]
	s_mov_b64 s[54:55], s[82:83]
	s_mov_b32 s52, s87
	s_mov_b32 s51, s86
	s_mov_b32 s8, s84
	s_mov_b64 s[16:17], 0
	v_mov_b32_e32 v8, v137
	v_mov_b64_e32 v[4:5], v[0:1]

; __device__ __forceinline__ void chunk_pre(const Params& p, LAS unsigned char* lds, int item, int next_item, int tid, int wave, int lane, h16 (&raw)[48]) {
;     ...
;     for (int e = tid; e < 3 * 256; e += 512) { const int bk = e >> 8, i = (e >> 4) & 15, j = e & 15; Wf[bk * 256 + i * 16 + j] = M16(bk + 1, bk, TD + bk * 256); }
.LBB0_937:
	v_bfe_u32 v20, v4, 4, 4
	v_ashrrev_i32_e32 v5, 8, v4
	v_lshlrev_b32_e32 v6, 8, v20
	v_lshl_or_b32 v6, v5, 12, v6
	v_lshlrev_b32_e32 v5, 6, v5
	v_add3_u32 v5, v6, s18, v5
	v_lshlrev_b32_e32 v6, 2, v4
	v_and_b32_e32 v163, 0xfffffc00, v6
	v_add_u32_e32 v168, v99, v163
	ds_read2_b32 v[18:19], v168 offset1:16
	ds_read2_b32 v[38:39], v168 offset0:32 offset1:48
	ds_read_b128 v[6:9], v5 offset:4096
	ds_read_b128 v[10:13], v5 offset:4112
	ds_read_b128 v[14:17], v5 offset:4128
	ds_read_b128 v[34:37], v5 offset:4144
	s_waitcnt lgkmcnt(5)
	v_mov_b32_e32 v166, v19
	s_waitcnt lgkmcnt(3)
	v_mov_b32_e32 v164, v7
	v_mov_b32_e32 v7, v9
	v_mov_b32_e32 v19, v39
	v_mov_b32_e32 v165, v8
	ds_read2_b32 v[8:9], v168 offset0:64 offset1:80
	ds_read2_b32 v[212:213], v168 offset0:96 offset1:112
	v_pk_mul_f32 v[6:7], v[6:7], v[18:19]
	s_nop 0
	s_nop 0
	v_mov_b32_e32 v167, v38
	v_pk_fma_f32 v[6:7], v[164:165], v[166:167], v[6:7]
	s_waitcnt lgkmcnt(4)
	v_mov_b32_e32 v38, v11
	s_waitcnt lgkmcnt(1)
	v_mov_b32_e32 v164, v9
	v_mov_b32_e32 v11, v13
	s_waitcnt lgkmcnt(0)
	v_mov_b32_e32 v9, v213
	v_mov_b32_e32 v39, v12
	v_mov_b32_e32 v165, v212
	v_pk_mul_f32 v[8:9], v[10:11], v[8:9]
	ds_read2_b32 v[10:11], v168 offset0:128 offset1:144
	ds_read2_b32 v[12:13], v168 offset0:160 offset1:176
	ds_read2_b32 v[18:19], v168 offset0:192 offset1:208
	ds_read2_b32 v[212:213], v168 offset0:224 offset1:240
	v_add_f32_e32 v5, v6, v7
	v_add_f32_e32 v6, 0, v5
	v_pk_fma_f32 v[8:9], v[38:39], v[164:165], v[8:9]
	v_cmp_lt_i32_e32 vcc, s44, v4
	s_waitcnt lgkmcnt(1)
	v_mul_f32_e32 v7, v34, v18
	v_mul_f32_e32 v5, v35, v19
	s_nop 0
	v_pk_add_f32 v[8:9], v[8:9], v[8:9] op_sel:[0,1] op_sel_hi:[1,0]
	s_or_b64 s[80:81], vcc, s[80:81]
	v_mov_b32_e32 v9, v5
	v_pk_add_f32 v[6:7], v[6:7], v[8:9]
	v_mul_f32_e32 v8, v15, v11
	v_pk_fma_f32 v[8:9], v[14:15], v[10:11], v[8:9] op_sel_hi:[1,1,0]
	v_mul_f32_e32 v10, v17, v13
	s_waitcnt lgkmcnt(0)
	v_mul_f32_e32 v18, v36, v212
	v_mul_f32_e32 v19, v37, v213
	v_pk_fma_f32 v[10:11], v[16:17], v[12:13], v[10:11] op_sel_hi:[1,1,0]
	v_mov_b32_e32 v9, v18
	v_mov_b32_e32 v11, v19
	v_pk_add_f32 v[8:9], v[8:9], v[10:11]
	s_nop 0
	v_pk_add_f32 v[6:7], v[6:7], v[8:9]
	s_nop 0
	v_add_f32_e32 v5, v6, v7
	v_add_u32_e32 v6, s42, v163
	v_lshlrev_b32_e32 v7, 6, v20
	v_add3_u32 v6, v6, v7, v98
	ds_write_b32 v6, v5
	v_add_u32_e32 v5, 0x200, v4
	v_mov_b32_e32 v4, v5
	s_andn2_b64 exec, exec, s[80:81]
	s_cbranch_execnz .LBB0_937

; #define BAR_LDS() do { asm volatile("s_waitcnt lgkmcnt(0)" ::: "memory"); __builtin_amdgcn_s_barrier(); asm volatile("" ::: "memory"); } while (0)
; __device__ __forceinline__ unsigned pk2(float lo, float hi) { const f32x2c v = {lo, hi}; const bf16x2c b = __builtin_convertvector(v, bf16x2c); return __builtin_bit_cast(unsigned, b); }
; #define TDW(r_, wp) ({ const LAS float* tr_ = TD + (r_) * 256 + i * 16; const LAS float* bp_ = (wp) + j; float a_ = 0.f; \
;         _Pragma("unroll") for (int u4 = 0; u4 < 4; ++u4) { const f32x4 t4 = *(const LAS f32x4*)(tr_ + 4 * u4); \
;             a_ += (t4.x * bp_[(4 * u4) * 16] + t4.y * bp_[(4 * u4 + 1) * 16]) + (t4.z * bp_[(4 * u4 + 2) * 16] + t4.w * bp_[(4 * u4 + 3) * 16]); } a_; })
; __device__ __forceinline__ void chunk_pre(const Params& p, LAS unsigned char* lds, int item, int next_item, int tid, int wave, int lane, h16 (&raw)[48]) {
;     ...
;     for (int e = tid; e < 3 * 256; e += 512) { const int bk = e >> 8, i = (e >> 4) & 15, j = e & 15; Wf[bk * 256 + i * 16 + j] = M16(bk + 1, bk, TD + bk * 256); }
;     BAR_LDS();
;     for (int e = tid; e < 3 * 256; e += 512) { const int bk = e >> 8, i = (e >> 4) & 15, j = e & 15; const float t = TDW(bk + 1, Wf + bk * 256);
;         Toff[bk * 256 + i * 16 + j] = t; Tb[(16 * (bk + 1) + i) * MS + 16 * bk + j] = (bf16_t)(pk2(t, 0.f) & 0xffffu); }
;     BAR_LDS();
;     { const int bk = tid >> 8, i = (tid >> 4) & 15, j = tid & 15; Wf[bk * 256 + i * 16 + j] = M16(bk + 2, bk, TD + bk * 256) + M16(bk + 2, bk + 1, Toff + bk * 256); }
.LBB0_940:
	v_ashrrev_i32_e32 v5, 8, v4
	v_bfe_u32 v20, v4, 4, 4
	v_add_u32_e32 v38, 1, v5
	v_lshlrev_b32_e32 v6, 10, v38
	v_lshlrev_b32_e32 v39, 6, v20
	v_add3_u32 v18, s19, v6, v39
	ds_read_b128 v[212:215], v18
	ds_read_b128 v[10:13], v18 offset:16
	ds_read_b128 v[14:17], v18 offset:32
	ds_read_b128 v[34:37], v18 offset:48
	v_lshlrev_b32_e32 v6, 2, v4
	v_and_b32_e32 v163, 0xfffffc00, v6
	v_add_u32_e32 v164, v118, v163
	s_nop 0
	s_nop 0
	s_nop 0
	s_nop 0
	ds_read2_b32 v[18:19], v164 offset1:16
	ds_read2_b32 v[216:217], v164 offset0:32 offset1:48
	ds_read2_b32 v[218:219], v164 offset0:64 offset1:80
	ds_read2_b32 v[220:221], v164 offset0:96 offset1:112
	ds_read2_b32 v[222:223], v164 offset0:128 offset1:144
	ds_read2_b32 v[224:225], v164 offset0:160 offset1:176
	ds_read2_b32 v[226:227], v164 offset0:192 offset1:208
	ds_read2_b32 v[228:229], v164 offset0:224 offset1:240
	v_lshlrev_b32_e32 v5, 5, v5
	v_cmp_lt_i32_e32 vcc, s44, v4
	s_or_b64 s[14:15], vcc, s[14:15]
	s_waitcnt lgkmcnt(7)
	v_mul_f32_e32 v19, v213, v19
	v_fmac_f32_e32 v19, v212, v18
	s_nop 0
	s_waitcnt lgkmcnt(6)
	v_mul_f32_e32 v7, v215, v217
	v_fmac_f32_e32 v7, v214, v216
	v_add_f32_e32 v6, v19, v7
	v_add_f32_e32 v8, 0, v6
	s_nop 0
	s_waitcnt lgkmcnt(5)
	v_mul_f32_e32 v9, v11, v219
	v_fmac_f32_e32 v9, v10, v218
	s_nop 0
	s_waitcnt lgkmcnt(4)
	v_mul_f32_e32 v7, v13, v221
	v_fmac_f32_e32 v7, v12, v220
	v_add_f32_e32 v6, v9, v7
	v_add_f32_e32 v8, v8, v6
	s_nop 0
	s_waitcnt lgkmcnt(3)
	v_mul_f32_e32 v9, v15, v223
	v_fmac_f32_e32 v9, v14, v222
	s_nop 0
	s_waitcnt lgkmcnt(2)
	v_mul_f32_e32 v7, v17, v225
	v_fmac_f32_e32 v7, v16, v224
	v_add_f32_e32 v6, v9, v7
	v_add_f32_e32 v8, v8, v6
	s_nop 0
	s_waitcnt lgkmcnt(1)
	v_mul_f32_e32 v9, v35, v227
	v_fmac_f32_e32 v9, v34, v226
	s_nop 0
	s_waitcnt lgkmcnt(0)
	v_mul_f32_e32 v7, v37, v229
	v_fmac_f32_e32 v7, v36, v228
	v_add_f32_e32 v6, v9, v7
	v_add_u32_e32 v7, s43, v163
	v_add_f32_e32 v6, v8, v6
	v_add3_u32 v7, v7, v39, v98
	ds_write_b32 v7, v6
	v_lshl_or_b32 v7, v38, 4, v20
	v_mul_lo_u32 v7, v7, s79
	v_add_u32_e32 v7, 0, v7
	v_cvt_pk_bf16_f32 v6, v6, s0
	v_add3_u32 v5, v7, v5, v100
	ds_write_b16 v5, v6
	v_add_u32_e32 v5, 0x200, v4
	v_mov_b32_e32 v4, v5
	s_andn2_b64 exec, exec, s[14:15]
	s_cbranch_execnz .LBB0_940
.LBB0_941:
	s_or_b64 exec, exec, s[12:13]
	s_waitcnt lgkmcnt(0)
	s_barrier
	ds_read_b128 v[4:7], v119
	ds_read_b128 v[8:11], v119 offset:16
	ds_read_b128 v[12:15], v119 offset:32
	ds_read_b128 v[16:19], v119 offset:48
	ds_read2_b32 v[34:35], v120 offset1:16
	ds_read2_b32 v[212:213], v120 offset0:32 offset1:48
	ds_read2_b32 v[214:215], v120 offset0:64 offset1:80
	ds_read2_b32 v[216:217], v120 offset0:96 offset1:112
	ds_read2_b32 v[218:219], v120 offset0:128 offset1:144
	ds_read2_b32 v[220:221], v120 offset0:160 offset1:176
	ds_read2_b32 v[222:223], v120 offset0:192 offset1:208
	ds_read2_b32 v[224:225], v120 offset0:224 offset1:240
	ds_read_b128 v[228:231], v119 offset:64
	s_waitcnt lgkmcnt(8)
	v_mul_f32_e32 v20, v5, v35
	v_fmac_f32_e32 v20, v4, v34
	s_nop 0
	s_waitcnt lgkmcnt(7)
	v_mul_f32_e32 v5, v7, v213
	v_fmac_f32_e32 v5, v6, v212
	v_add_f32_e32 v20, v20, v5
	s_nop 0
	s_waitcnt lgkmcnt(6)
	v_mul_f32_e32 v6, v9, v215
	v_fmac_f32_e32 v6, v8, v214
	s_nop 0
	s_waitcnt lgkmcnt(5)
	v_mul_f32_e32 v5, v11, v217
	v_fmac_f32_e32 v5, v10, v216
	ds_read_b128 v[8:11], v119 offset:80
	v_add_f32_e32 v36, v6, v5
	s_nop 0
	s_waitcnt lgkmcnt(5)
	v_mul_f32_e32 v6, v13, v219
	v_fmac_f32_e32 v6, v12, v218
	s_nop 0
	s_waitcnt lgkmcnt(4)
	v_mul_f32_e32 v5, v15, v221
	v_fmac_f32_e32 v5, v14, v220
	ds_read_b128 v[12:15], v119 offset:96
	v_add_f32_e32 v37, v6, v5
	s_nop 0
	s_waitcnt lgkmcnt(4)
	v_mul_f32_e32 v6, v17, v223
	v_fmac_f32_e32 v6, v16, v222
	s_nop 0
	s_waitcnt lgkmcnt(3)
	v_mul_f32_e32 v5, v19, v225
	v_fmac_f32_e32 v5, v18, v224
	ds_read_b128 v[16:19], v119 offset:112
	ds_read2_b32 v[34:35], v122 offset1:16
	ds_read2_b32 v[212:213], v122 offset0:32 offset1:48
	ds_read2_b32 v[214:215], v122 offset0:64 offset1:80
	ds_read2_b32 v[216:217], v122 offset0:96 offset1:112
	ds_read2_b32 v[218:219], v122 offset0:128 offset1:144
	ds_read2_b32 v[220:221], v122 offset0:160 offset1:176
	ds_read2_b32 v[222:223], v122 offset0:192 offset1:208
	ds_read2_b32 v[224:225], v122 offset0:224 offset1:240
	v_add_f32_e32 v38, v6, v5
	s_nop 0
	s_nop 0
	s_nop 0
	s_nop 0
	s_nop 0
	s_waitcnt lgkmcnt(7)
	v_mul_f32_e32 v35, v229, v35
	v_fmac_f32_e32 v35, v228, v34
	s_nop 0
	s_waitcnt lgkmcnt(6)
	v_mul_f32_e32 v5, v231, v213
	v_fmac_f32_e32 v5, v230, v212
	v_add_f32_e32 v4, v35, v5
	v_add_f32_e32 v6, 0, v4
	s_nop 0
	s_waitcnt lgkmcnt(5)
	v_mul_f32_e32 v7, v9, v215
	v_fmac_f32_e32 v7, v8, v214
	s_nop 0
	s_waitcnt lgkmcnt(4)
	v_mul_f32_e32 v5, v11, v217
	v_fmac_f32_e32 v5, v10, v216
	v_add_f32_e32 v4, v7, v5
	v_add_f32_e32 v6, v6, v4
	s_nop 0
	s_waitcnt lgkmcnt(3)
	v_mul_f32_e32 v7, v13, v219
	v_fmac_f32_e32 v7, v12, v218
	s_nop 0
	s_waitcnt lgkmcnt(2)
	v_mul_f32_e32 v5, v15, v221
	v_fmac_f32_e32 v5, v14, v220
	v_add_f32_e32 v4, v7, v5
	v_add_f32_e32 v6, v6, v4
	s_nop 0
	s_waitcnt lgkmcnt(1)
	v_mul_f32_e32 v7, v17, v223
	v_fmac_f32_e32 v7, v16, v222
	s_nop 0
	s_waitcnt lgkmcnt(0)
	v_mul_f32_e32 v5, v19, v225
	v_fmac_f32_e32 v5, v18, v224
	v_add_f32_e32 v4, v7, v5
	v_add_f32_e32 v5, 0, v20
	v_add_f32_e32 v5, v5, v36
	v_add_f32_e32 v5, v5, v37
	v_add_f32_e32 v4, v6, v4
	v_add_f32_e32 v5, v5, v38
	v_add_f32_e32 v4, v5, v4
	ds_write_b32 v124, v4
	s_waitcnt lgkmcnt(0)
	s_barrier
; #define BAR_LDS() do { asm volatile("s_waitcnt lgkmcnt(0)" ::: "memory"); __builtin_amdgcn_s_barrier(); asm volatile("" ::: "memory"); } while (0)
; __device__ __forceinline__ unsigned pk2(float lo, float hi) { const f32x2c v = {lo, hi}; const bf16x2c b = __builtin_convertvector(v, bf16x2c); return __builtin_bit_cast(unsigned, b); }
; #define TDW(r_, wp) ({ const LAS float* tr_ = TD + (r_) * 256 + i * 16; const LAS float* bp_ = (wp) + j; float a_ = 0.f; \
;         _Pragma("unroll") for (int u4 = 0; u4 < 4; ++u4) { const f32x4 t4 = *(const LAS f32x4*)(tr_ + 4 * u4); \
;             a_ += (t4.x * bp_[(4 * u4) * 16] + t4.y * bp_[(4 * u4 + 1) * 16]) + (t4.z * bp_[(4 * u4 + 2) * 16] + t4.w * bp_[(4 * u4 + 3) * 16]); } a_; })
; __device__ __forceinline__ void chunk_pre(const Params& p, LAS unsigned char* lds, int item, int next_item, int tid, int wave, int lane, h16 (&raw)[48]) {
;     ...
;     for (int e = tid; e < 3 * 256; e += 512) { const int bk = e >> 8, i = (e >> 4) & 15, j = e & 15; const float t = TDW(bk + 1, Wf + bk * 256);
;         Toff[bk * 256 + i * 16 + j] = t; Tb[(16 * (bk + 1) + i) * MS + 16 * bk + j] = (bf16_t)(pk2(t, 0.f) & 0xffffu); }
;     BAR_LDS();
;     { const int bk = tid >> 8, i = (tid >> 4) & 15, j = tid & 15; Wf[bk * 256 + i * 16 + j] = M16(bk + 2, bk, TD + bk * 256) + M16(bk + 2, bk + 1, Toff + bk * 256); }
;     BAR_LDS();
;     { const int bk = tid >> 8, i = (tid >> 4) & 15, j = tid & 15; const float t = TDW(bk + 2, Wf + bk * 256);
;       Toff[(3 + bk) * 256 + i * 16 + j] = t; Tb[(16 * (bk + 2) + i) * MS + 16 * bk + j] = (bf16_t)(pk2(t, 0.f) & 0xffffu); }
;     BAR_LDS();
;     if (tid < 256) { const int i = tid >> 4, j = tid & 15; Wf[i * 16 + j] = M16(3, 0, TD) + M16(3, 1, Toff) + M16(3, 2, Toff + 3 * 256); }
;     BAR_LDS();
;     if (tid < 256) { const int i = tid >> 4, j = tid & 15; const float t = TDW(3, Wf); Tb[(48 + i) * MS + j] = (bf16_t)(pk2(t, 0.f) & 0xffffu); }
	ds_read_b128 v[4:7], v125
	ds_read_b128 v[8:11], v125 offset:16
	ds_read_b128 v[12:15], v125 offset:32
	ds_read_b128 v[16:19], v125 offset:48
	ds_read2_b32 v[34:35], v123 offset1:16
	ds_read2_b32 v[212:213], v123 offset0:32 offset1:48
	ds_read2_b32 v[214:215], v123 offset0:64 offset1:80
	ds_read2_b32 v[216:217], v123 offset0:96 offset1:112
	ds_read2_b32 v[218:219], v123 offset0:128 offset1:144
	ds_read2_b32 v[220:221], v123 offset0:160 offset1:176
	ds_read2_b32 v[222:223], v123 offset0:192 offset1:208
	ds_read2_b32 v[224:225], v123 offset0:224 offset1:240
	s_waitcnt lgkmcnt(7)
	v_mul_f32_e32 v20, v5, v35
	v_fmac_f32_e32 v20, v4, v34
	s_nop 0
	s_waitcnt lgkmcnt(6)
	v_mul_f32_e32 v5, v7, v213
	v_fmac_f32_e32 v5, v6, v212
	v_add_f32_e32 v4, v20, v5
	v_add_f32_e32 v6, 0, v4
	s_nop 0
	s_waitcnt lgkmcnt(5)
	v_mul_f32_e32 v7, v9, v215
	v_fmac_f32_e32 v7, v8, v214
	s_nop 0
	s_waitcnt lgkmcnt(4)
	v_mul_f32_e32 v5, v11, v217
	v_fmac_f32_e32 v5, v10, v216
	v_add_f32_e32 v4, v7, v5
	v_add_f32_e32 v6, v6, v4
	s_nop 0
	s_waitcnt lgkmcnt(3)
	v_mul_f32_e32 v7, v13, v219
	v_fmac_f32_e32 v7, v12, v218
	s_nop 0
	s_waitcnt lgkmcnt(2)
	v_mul_f32_e32 v5, v15, v221
	v_fmac_f32_e32 v5, v14, v220
	v_add_f32_e32 v4, v7, v5
	v_add_f32_e32 v6, v6, v4
	s_nop 0
	s_waitcnt lgkmcnt(1)
	v_mul_f32_e32 v7, v17, v223
	v_fmac_f32_e32 v7, v16, v222
	s_nop 0
	s_waitcnt lgkmcnt(0)
	v_mul_f32_e32 v5, v19, v225
	v_fmac_f32_e32 v5, v18, v224
	v_add_f32_e32 v4, v7, v5
	v_add_f32_e32 v4, v6, v4
	ds_write_b32 v126, v4 offset:3072
	v_cvt_pk_bf16_f32 v4, v4, s0
	ds_write_b16 v127, v4
	s_waitcnt lgkmcnt(0)
	s_barrier
	s_and_saveexec_b64 s[12:13], s[48:49]
	s_cbranch_execz .LBB0_943
	ds_read2_b32 v[34:35], v99 offset1:16
	ds_read2_b32 v[36:37], v99 offset0:32 offset1:48
	ds_read_b128 v[16:19], v162 offset:12288
	ds_read_b128 v[12:15], v162 offset:12304
	ds_read_b128 v[8:11], v162 offset:12320
	ds_read_b128 v[4:7], v162 offset:12336
	ds_read2_b32 v[184:185], v99 offset0:64 offset1:80
	ds_read2_b32 v[212:213], v99 offset0:96 offset1:112
	ds_read2_b32 v[214:215], v99 offset0:128 offset1:144
	s_nop 0
	s_nop 0
	s_nop 0
	s_nop 0
	s_nop 0
	s_nop 0
	s_waitcnt lgkmcnt(8)
	v_mov_b32_e32 v164, v35
	s_waitcnt lgkmcnt(6)
	v_mov_b32_e32 v38, v17
	v_mov_b32_e32 v17, v19
	v_mov_b32_e32 v35, v37
	v_mov_b32_e32 v39, v18
	v_mov_b32_e32 v165, v36
	v_pk_mul_f32 v[16:17], v[16:17], v[34:35]
	ds_read2_b32 v[34:35], v99 offset0:160 offset1:176
	ds_read2_b32 v[18:19], v99 offset0:192 offset1:208
	s_nop 0
	v_pk_fma_f32 v[16:17], v[38:39], v[164:165], v[16:17]
	s_nop 0
	v_add_f32_e32 v20, v16, v17
	ds_read2_b32 v[16:17], v99 offset0:224 offset1:240
	ds_read_b128 v[164:167], v162 offset:12352
	ds_read2_b32 v[172:173], v121 offset1:16
	ds_read2_b32 v[174:175], v121 offset0:32 offset1:48
	ds_read_b128 v[168:171], v162 offset:12368
	ds_read2_b32 v[176:177], v121 offset0:64 offset1:80
	ds_read2_b32 v[178:179], v121 offset0:96 offset1:112
	s_nop 0
	s_nop 0
	s_nop 0
	s_nop 0
	s_nop 0
	s_nop 0
	s_nop 0
	s_nop 0
	s_nop 0
	s_nop 0
	s_nop 0
	s_nop 0
	s_waitcnt lgkmcnt(5)
	v_mov_b32_e32 v180, v164
	s_waitcnt lgkmcnt(4)
	v_mov_b32_e32 v182, v172
	s_waitcnt lgkmcnt(2)
	v_mov_b32_e32 v181, v168
	s_waitcnt lgkmcnt(1)
	v_mov_b32_e32 v183, v176
	v_mov_b32_e32 v168, v165
	v_mov_b32_e32 v176, v173
	v_pk_mul_f32 v[164:165], v[168:169], v[176:177]
	v_mov_b32_e32 v169, v170
	s_waitcnt lgkmcnt(0)
	v_mov_b32_e32 v173, v178
	v_mov_b32_e32 v170, v167
	v_mov_b32_e32 v178, v175
	v_mov_b32_e32 v168, v166
	v_mov_b32_e32 v172, v174
	v_pk_mul_f32 v[166:167], v[170:171], v[178:179]
	v_pk_fma_f32 v[164:165], v[180:181], v[182:183], v[164:165]
	v_pk_fma_f32 v[166:167], v[168:169], v[172:173], v[166:167]
	v_add_f32_e32 v20, 0, v20
	v_pk_add_f32 v[186:187], v[164:165], v[166:167]
	ds_read_b128 v[164:167], v162 offset:12384
	ds_read2_b32 v[168:169], v121 offset0:128 offset1:144
	ds_read2_b32 v[170:171], v121 offset0:160 offset1:176
	s_waitcnt lgkmcnt(2)
	v_mov_b32_e32 v172, v165
	s_waitcnt lgkmcnt(1)
	v_mov_b32_e32 v174, v169
	v_mov_b32_e32 v165, v167
	s_waitcnt lgkmcnt(0)
	v_mov_b32_e32 v169, v171
	v_mov_b32_e32 v173, v166
	v_mov_b32_e32 v175, v170
	v_pk_mul_f32 v[164:165], v[164:165], v[168:169]
	s_nop 0
	v_pk_fma_f32 v[188:189], v[172:173], v[174:175], v[164:165]
	ds_read_b128 v[164:167], v162 offset:12400
	ds_read2_b32 v[190:191], v121 offset0:192 offset1:208
	ds_read2_b32 v[192:193], v121 offset0:224 offset1:240
	ds_read_b128 v[168:171], v162 offset:12416
	ds_read2_b32 v[194:195], v128 offset1:16
	ds_read2_b32 v[196:197], v128 offset0:32 offset1:48
	ds_read_b128 v[172:175], v162 offset:12432
	ds_read2_b32 v[198:199], v128 offset0:64 offset1:80
	ds_read2_b32 v[200:201], v128 offset0:96 offset1:112
	ds_read_b128 v[176:179], v162 offset:12448
	ds_read2_b32 v[202:203], v128 offset0:128 offset1:144
	ds_read2_b32 v[206:207], v128 offset0:160 offset1:176
	ds_read_b128 v[180:183], v162 offset:12464
	ds_read2_b32 v[208:209], v128 offset0:192 offset1:208
	ds_read2_b32 v[216:217], v128 offset0:224 offset1:240
	s_waitcnt lgkmcnt(1)
; #define BAR_LDS() do { asm volatile("s_waitcnt lgkmcnt(0)" ::: "memory"); __builtin_amdgcn_s_barrier(); asm volatile("" ::: "memory"); } while (0)
; __device__ __forceinline__ unsigned pk2(float lo, float hi) { const f32x2c v = {lo, hi}; const bf16x2c b = __builtin_convertvector(v, bf16x2c); return __builtin_bit_cast(unsigned, b); }
; #define TDW(r_, wp) ({ const LAS float* tr_ = TD + (r_) * 256 + i * 16; const LAS float* bp_ = (wp) + j; float a_ = 0.f; \
;         _Pragma("unroll") for (int u4 = 0; u4 < 4; ++u4) { const f32x4 t4 = *(const LAS f32x4*)(tr_ + 4 * u4); \
;             a_ += (t4.x * bp_[(4 * u4) * 16] + t4.y * bp_[(4 * u4 + 1) * 16]) + (t4.z * bp_[(4 * u4 + 2) * 16] + t4.w * bp_[(4 * u4 + 3) * 16]); } a_; })
; __device__ __forceinline__ void chunk_pre(const Params& p, LAS unsigned char* lds, int item, int next_item, int tid, int wave, int lane, h16 (&raw)[48]) {
;     ...
;     if (tid < 256) { const int i = tid >> 4, j = tid & 15; Wf[i * 16 + j] = M16(3, 0, TD) + M16(3, 1, Toff) + M16(3, 2, Toff + 3 * 256); }
;     BAR_LDS();
;     if (tid < 256) { const int i = tid >> 4, j = tid & 15; const float t = TDW(3, Wf); Tb[(48 + i) * MS + j] = (bf16_t)(pk2(t, 0.f) & 0xffffu); }
;     BAR_LDS();
	v_mul_f32_e32 v211, v180, v208
	v_mul_f32_e32 v163, v181, v209
	s_nop 0
	s_waitcnt lgkmcnt(0)
	v_mul_f32_e32 v205, v182, v216
	v_mul_f32_e32 v208, v183, v217
	v_add_f32_e32 v180, 0, v186
	v_mov_b32_e32 v181, v168
	v_mov_b32_e32 v183, v194
	v_mov_b32_e32 v168, v13
	v_mov_b32_e32 v194, v185
	v_add_f32_e32 v210, v180, v187
	v_mov_b32_e32 v180, v12
	v_mov_b32_e32 v182, v184
	v_pk_mul_f32 v[12:13], v[168:169], v[194:195]
	v_mov_b32_e32 v169, v170
	v_pk_fma_f32 v[12:13], v[180:181], v[182:183], v[12:13]
	v_mov_b32_e32 v181, v196
	v_mov_b32_e32 v170, v15
	v_mov_b32_e32 v196, v213
	v_mov_b32_e32 v168, v14
	v_mov_b32_e32 v180, v212
	v_pk_mul_f32 v[14:15], v[170:171], v[196:197]
	v_mov_b32_e32 v39, v198
	v_pk_fma_f32 v[14:15], v[168:169], v[180:181], v[14:15]
	v_mov_b32_e32 v198, v215
	v_pk_add_f32 v[12:13], v[12:13], v[14:15]
	v_mov_b32_e32 v15, v172
	v_mov_b32_e32 v172, v9
	v_mov_b32_e32 v14, v8
	v_mov_b32_e32 v38, v214
	v_pk_mul_f32 v[8:9], v[172:173], v[198:199]
	v_mov_b32_e32 v37, v200
	v_pk_fma_f32 v[8:9], v[14:15], v[38:39], v[8:9]
	v_mov_b32_e32 v15, v174
	v_mov_b32_e32 v174, v11
	v_mov_b32_e32 v200, v35
	v_mov_b32_e32 v14, v10
	v_mov_b32_e32 v36, v34
	v_pk_mul_f32 v[10:11], v[174:175], v[200:201]
	v_pk_add_f32 v[12:13], v[12:13], v[20:21]
	v_pk_fma_f32 v[10:11], v[14:15], v[36:37], v[10:11]
	s_nop 0
	v_pk_add_f32 v[8:9], v[8:9], v[10:11]
	v_mov_b32_e32 v11, v176
	v_pk_add_f32 v[8:9], v[12:13], v[8:9]
	v_mov_b32_e32 v13, v202
	v_mov_b32_e32 v176, v5
	v_mov_b32_e32 v202, v19
	v_mov_b32_e32 v10, v4
	v_mov_b32_e32 v12, v18
	v_pk_mul_f32 v[4:5], v[176:177], v[202:203]
	s_nop 0
	v_pk_fma_f32 v[4:5], v[10:11], v[12:13], v[4:5]
	v_mov_b32_e32 v11, v178
	v_mov_b32_e32 v13, v206
	v_mov_b32_e32 v178, v7
	v_mov_b32_e32 v206, v17
	v_mov_b32_e32 v10, v6
	v_mov_b32_e32 v12, v16
	v_pk_mul_f32 v[6:7], v[178:179], v[206:207]
	s_nop 0
	v_pk_fma_f32 v[6:7], v[10:11], v[12:13], v[6:7]
	s_nop 0
	v_pk_add_f32 v[4:5], v[4:5], v[6:7]
	v_mul_f32_e32 v6, v165, v191
	v_pk_add_f32 v[4:5], v[8:9], v[4:5]
	v_mul_f32_e32 v8, v167, v193
	v_pk_fma_f32 v[6:7], v[164:165], v[190:191], v[6:7] op_sel_hi:[1,1,0]
	v_pk_fma_f32 v[8:9], v[166:167], v[192:193], v[8:9] op_sel_hi:[1,1,0]
	v_mov_b32_e32 v7, v205
	v_mov_b32_e32 v9, v208
	v_pk_add_f32 v[6:7], v[6:7], v[8:9]
	v_pk_add_f32 v[8:9], v[188:189], v[188:189] op_sel:[0,1] op_sel_hi:[1,0]
	s_nop 0
	v_mov_b32_e32 v9, v163
	v_pk_add_f32 v[8:9], v[210:211], v[8:9]
	s_nop 0
	v_pk_add_f32 v[6:7], v[8:9], v[6:7]
	s_nop 0
	v_pk_add_f32 v[4:5], v[4:5], v[6:7]
	s_nop 0
	v_add_f32_e32 v4, v4, v5
	ds_write_b32 v129, v4
.LBB0_943:
	s_or_b64 exec, exec, s[12:13]
	s_waitcnt lgkmcnt(0)
	s_barrier
	s_and_saveexec_b64 s[12:13], s[48:49]
	s_cbranch_execz .LBB0_922
	ds_read2_b32 v[34:35], v118 offset1:16
	ds_read_b128 v[4:7], v130
	ds_read2_b32 v[36:37], v118 offset0:32 offset1:48
	ds_read_b128 v[8:11], v130 offset:16
	ds_read_b128 v[12:15], v130 offset:32
	ds_read_b128 v[16:19], v130 offset:48
	s_nop 0
	s_nop 0
	s_nop 0
	s_nop 0
	s_nop 0
	s_nop 0
	s_waitcnt lgkmcnt(4)
	v_mov_b32_e32 v38, v5
	v_mov_b32_e32 v164, v35
	v_mov_b32_e32 v5, v7
	s_waitcnt lgkmcnt(3)
	v_mov_b32_e32 v35, v37
	v_mov_b32_e32 v39, v6
	v_mov_b32_e32 v165, v36
	v_pk_mul_f32 v[4:5], v[4:5], v[34:35]
	s_waitcnt lgkmcnt(2)
	v_mov_b32_e32 v36, v9
	v_pk_fma_f32 v[4:5], v[38:39], v[164:165], v[4:5]
	v_mov_b32_e32 v9, v11
	v_add_f32_e32 v20, v4, v5
	ds_read2_b32 v[4:5], v118 offset0:64 offset1:80
	ds_read2_b32 v[6:7], v118 offset0:96 offset1:112
	v_mov_b32_e32 v37, v10
	v_add_f32_e32 v34, 0, v20
	s_waitcnt lgkmcnt(1)
	v_mov_b32_e32 v38, v5
	s_waitcnt lgkmcnt(0)
	v_mov_b32_e32 v39, v6
	v_mov_b32_e32 v5, v7
	ds_read2_b32 v[6:7], v118 offset0:192 offset1:208
	v_pk_mul_f32 v[4:5], v[8:9], v[4:5]
	ds_read2_b32 v[8:9], v118 offset0:224 offset1:240
	ds_read2_b32 v[10:11], v118 offset0:128 offset1:144
	s_waitcnt lgkmcnt(2)
	v_mul_f32_e32 v35, v16, v6
	v_pk_fma_f32 v[4:5], v[36:37], v[38:39], v[4:5]
	ds_read2_b32 v[36:37], v118 offset0:160 offset1:176
	s_nop 0
	s_nop 0
	s_nop 0
	v_mul_f32_e32 v6, v17, v7
	v_pk_add_f32 v[4:5], v[4:5], v[4:5] op_sel:[0,1] op_sel_hi:[1,0]
	s_waitcnt lgkmcnt(2)
	v_mul_f32_e32 v8, v18, v8
	v_mov_b32_e32 v5, v6
	s_waitcnt lgkmcnt(1)
	v_mul_f32_e32 v6, v13, v11
	v_pk_fma_f32 v[6:7], v[12:13], v[10:11], v[6:7] op_sel_hi:[1,1,0]
	v_mul_f32_e32 v16, v19, v9
	v_mov_b32_e32 v7, v8
	s_waitcnt lgkmcnt(0)
	v_mul_f32_e32 v8, v15, v37
	v_pk_fma_f32 v[8:9], v[14:15], v[36:37], v[8:9] op_sel_hi:[1,1,0]
	v_pk_add_f32 v[4:5], v[34:35], v[4:5]
	v_mov_b32_e32 v9, v16
	v_pk_add_f32 v[6:7], v[6:7], v[8:9]
	s_nop 0
	v_pk_add_f32 v[4:5], v[4:5], v[6:7]
	s_nop 0
	v_add_f32_e32 v4, v4, v5
	v_cvt_pk_bf16_f32 v4, v4, s0
	ds_write_b16 v131, v4 offset:6912
	s_branch .LBB0_922
